# static s_setprio 1 for waves 4-7 also at cross-attention phase entry
# baseline (speedup 1.0000x reference)
; #define INP(k) ((const float*)(const GASP float*)ldptr(PT, (k)))
; #define WSP(T, off) ((T*)(GASP T*)(ldptr(PT, 26) + (off)))
; __global__ void __launch_bounds__(NT, 2) trunk_fwd(Args args) {
;     ...
;         if (IN(pb + 4)) {
;             if (G % 16 == 0) {
;                 const int rem = bx % 16, nq = (32 - bx / 16 + G / 16 - 1) / (G / 16);
;     ...
;                 if (bx / 16 < 32) cross_unit(lds, WSP(bf16, WS_CQ), WSP(bf16, WS_CKV), INP(18) + layer * 128, INP(19) + layer * 128, layer, rem / 4, rem % 4, bx / 16, G / 16, nq);
.LBB0_963:
	s_cmp_le_i32 s18, s4
	s_cselect_b64 s[0:1], -1, 0
	s_cmp_lt_i32 s4, s19
	s_cselect_b64 s[4:5], -1, 0
	s_and_b64 s[4:5], s[0:1], s[4:5]
	s_mov_b64 s[0:1], -1
	s_and_b64 vcc, exec, s[4:5]
	s_cbranch_vccnz .LBB0_965
	s_or_b32 s4, s58, 6
	s_mov_b64 s[0:1], 0
.LBB0_965:
	s_andn2_b64 vcc, exec, s[0:1]
	s_cbranch_vccnz .LBB0_1047
	v_readfirstlane_b32 s0, v232
	s_nop 0
	s_lshr_b32 s0, s0, 6
	s_cmp_ge_u32 s0, 4
	s_cbranch_scc0 .Lprio_cx_done
	s_setprio 1
.Lprio_cx_done:
	v_readlane_b32 s0, v254, 12
	v_readlane_b32 s1, v254, 13
	s_andn2_b64 vcc, exec, s[0:1]
	s_cbranch_vccnz .LBB0_980
	s_and_b64 vcc, exec, s[70:71]
	s_cbranch_vccnz .LBB0_978
	s_lshl_b32 s86, s74, 7
	s_lshl_b32 s10, s74, 10
	s_mov_b32 s11, s2
	s_branch .LBB0_970
